# attention tile loop: the lane-half exchange of the per-tile row maximum (copy + permlane swap + max) moved into the rare new-maximum path; the common path tests the per-half maxima wave-wide
# speedup vs baseline: 1.0251x; 1.0047x over previous
.LBB0_423:
	s_lshl_b32 s16, s19, 14
	s_add_i32 s4, s16, 16
	v_add_u32_e32 v96, s4, v185
	ds_read_b128 v[198:201], v96 offset:49152
	ds_read_b128 v[202:205], v96 offset:57344
	v_xor_b32_e32 v80, 0x80000000, v195
	v_mov_b32_e32 v81, v80
	v_mov_b64_e32 v[82:83], v[80:81]
	v_mov_b64_e32 v[84:85], v[80:81]
	v_mov_b64_e32 v[86:87], v[80:81]
	v_mov_b64_e32 v[88:89], v[80:81]
	v_mov_b64_e32 v[90:91], v[80:81]
	v_mov_b64_e32 v[92:93], v[80:81]
	v_mov_b64_e32 v[94:95], v[80:81]
	v_exp_f32_e32 v221, v64
	s_waitcnt lgkmcnt(1)
	v_mfma_f32_32x32x16_bf16 v[96:111], v[198:201], v[124:127], v[80:95]
	v_add_f32_e32 v64, v153, v152
	v_add_f32_e32 v64, v154, v64
	v_add_u32_e32 v197, s4, v189
	v_add_f32_e32 v64, v155, v64
	v_add_f32_e32 v64, v156, v64
	v_add_f32_e32 v64, v157, v64
	v_add_f32_e32 v64, v158, v64
	s_waitcnt lgkmcnt(0)
	v_mfma_f32_32x32x16_bf16 v[80:95], v[202:205], v[124:127], v[80:95]
	ds_read_b128 v[198:201], v197 offset:49152
	ds_read_b128 v[202:205], v197 offset:57344
	v_add_f32_e32 v64, v159, v64
	v_add_f32_e32 v64, v144, v64
	v_add_f32_e32 v64, v145, v64
	v_add_f32_e32 v64, v146, v64
	v_add_u32_e32 v197, s4, v192
	v_add_f32_e32 v64, v147, v64
	s_waitcnt lgkmcnt(1)
	v_mfma_f32_32x32x16_bf16 v[96:111], v[198:201], v[120:123], v[96:111]
	ds_read_b128 v[198:201], v197 offset:49152
	ds_read_b128 v[206:209], v197 offset:57344
	v_add_f32_e32 v64, v148, v64
	v_exp_f32_e32 v222, v65
	v_add_f32_e32 v64, v149, v64
	v_exp_f32_e32 v223, v66
	v_add_f32_e32 v64, v150, v64
	v_exp_f32_e32 v224, v67
	s_waitcnt lgkmcnt(2)
	v_mfma_f32_32x32x16_bf16 v[80:95], v[202:205], v[120:123], v[80:95]
	v_add_f32_e32 v64, v151, v64
	v_add_f32_e32 v64, v221, v64
	v_add_f32_e32 v64, v222, v64
	v_add_f32_e32 v64, v223, v64
	v_exp_f32_e32 v71, v71
	v_add_f32_e32 v64, v224, v64
	v_add_u32_e32 v197, s4, v194
	s_waitcnt lgkmcnt(1)
	v_mfma_f32_32x32x16_bf16 v[96:111], v[198:201], v[116:119], v[96:111]
	v_exp_f32_e32 v199, v68
	v_exp_f32_e32 v200, v69
	v_exp_f32_e32 v201, v70
	v_exp_f32_e32 v225, v72
	v_add_f32_e32 v64, v199, v64
	ds_read_b128 v[202:205], v197 offset:49152
	ds_read_b128 v[210:213], v197 offset:57344
	v_exp_f32_e32 v226, v73
	s_waitcnt lgkmcnt(2)
	v_mfma_f32_32x32x16_bf16 v[80:95], v[206:209], v[116:119], v[80:95]
	v_add_f32_e32 v64, v200, v64
	v_exp_f32_e32 v227, v74
	v_add_f32_e32 v64, v201, v64
	v_exp_f32_e32 v206, v75
	v_add_f32_e32 v64, v71, v64
	v_exp_f32_e32 v207, v76
	v_add_f32_e32 v64, v225, v64
	v_exp_f32_e32 v208, v77
	v_add_f32_e32 v64, v226, v64
	v_exp_f32_e32 v209, v78
	s_waitcnt lgkmcnt(1)
	v_mfma_f32_32x32x16_bf16 v[96:111], v[202:205], v[112:115], v[96:111]
	v_add_f32_e32 v64, v227, v64
	v_exp_f32_e32 v79, v79
	v_add_f32_e32 v64, v206, v64
	v_add_f32_e32 v64, v207, v64
	v_add_f32_e32 v64, v208, v64
	v_add_f32_e32 v64, v209, v64
	v_add_f32_e32 v197, v79, v64
	s_waitcnt lgkmcnt(0)
	v_mfma_f32_32x32x16_bf16 v[80:95], v[210:213], v[112:115], v[80:95]
	v_cvt_pk_bf16_f32 v64, v152, v153
	v_cvt_pk_bf16_f32 v65, v154, v155
	v_cvt_pk_bf16_f32 v66, v156, v157
	v_cvt_pk_bf16_f32 v67, v158, v159
	v_cvt_pk_bf16_f32 v72, v144, v145
	v_cvt_pk_bf16_f32 v73, v146, v147
	v_cvt_pk_bf16_f32 v74, v148, v149
	v_cvt_pk_bf16_f32 v75, v150, v151
	v_cvt_pk_bf16_f32 v68, v221, v222
	v_cvt_pk_bf16_f32 v69, v223, v224
	v_cvt_pk_bf16_f32 v70, v199, v200
	v_cvt_pk_bf16_f32 v71, v201, v71
	v_cvt_pk_bf16_f32 v76, v225, v226
	v_cvt_pk_bf16_f32 v77, v227, v206
	v_cvt_pk_bf16_f32 v78, v207, v208
	v_cvt_pk_bf16_f32 v79, v209, v79
	global_load_dwordx4 v[144:147], v244, s[98:99]
	global_load_dwordx4 v[148:151], v245, s[98:99]
	global_load_dwordx4 v[152:155], v242, s[98:99]
	global_load_dwordx4 v[156:159], v243, s[98:99]
	s_add_u32 s98, s98, 0x10000
	s_addc_u32 s99, s99, 0
	v_lshl_add_u32 v199, s18, 14, v181
	ds_read_b64_tr_b16 v[200:201], v199 offset:0
	ds_read_b64_tr_b16 v[202:203], v199 offset:0x100
	ds_read_b64_tr_b16 v[204:205], v199 offset:0x1000
	ds_read_b64_tr_b16 v[206:207], v199 offset:0x1100
	ds_read_b64_tr_b16 v[208:209], v199 offset:0x2000
	ds_read_b64_tr_b16 v[210:211], v199 offset:0x2100
	ds_read_b64_tr_b16 v[222:223], v199 offset:0x3000
	ds_read_b64_tr_b16 v[224:225], v199 offset:0x3100
	s_nop 0
	s_waitcnt lgkmcnt(6)
	v_mfma_f32_32x32x16_bf16 v[0:15], v[64:67], v[200:203], v[0:15]
	v_max_f32_e32 v200, v96, v97
	v_max3_f32 v200, v200, v98, v99
	v_max3_f32 v200, v200, v100, v101
	v_max3_f32 v200, v200, v102, v103
	v_max3_f32 v200, v200, v104, v105
	s_waitcnt lgkmcnt(4)
	v_mfma_f32_32x32x16_bf16 v[0:15], v[72:75], v[204:207], v[0:15]
	v_max3_f32 v200, v200, v106, v107
	v_max3_f32 v202, v200, v108, v109
	ds_read_b64_tr_b16 v[200:201], v199 offset:0x200
	v_max3_f32 v212, v202, v110, v111
	ds_read_b64_tr_b16 v[202:203], v199 offset:0x300
	ds_read_b64_tr_b16 v[204:205], v199 offset:0x1200
	ds_read_b64_tr_b16 v[206:207], v199 offset:0x1300
	s_waitcnt lgkmcnt(6)
	v_mfma_f32_32x32x16_bf16 v[0:15], v[68:71], v[208:211], v[0:15]
	ds_read_b64_tr_b16 v[208:209], v199 offset:0x2200
	ds_read_b64_tr_b16 v[210:211], v199 offset:0x2300
	ds_read_b64_tr_b16 v[226:227], v199 offset:0x3200
	ds_read_b64_tr_b16 v[228:229], v199 offset:0x3300
	s_waitcnt lgkmcnt(8)
	v_mfma_f32_32x32x16_bf16 v[0:15], v[76:79], v[222:225], v[0:15]
	s_waitcnt lgkmcnt(6)
	v_mfma_f32_32x32x16_bf16 v[48:63], v[64:67], v[200:203], v[48:63]
	v_max3_f32 v212, v212, v80, v81
	v_max3_f32 v200, v212, v82, v83
	ds_read_b64_tr_b16 v[202:203], v199 offset:0x400
	v_max3_f32 v200, v200, v84, v85
	v_max3_f32 v200, v200, v86, v87
	v_max3_f32 v200, v200, v88, v89
	v_max3_f32 v200, v200, v90, v91
	s_waitcnt lgkmcnt(5)
	v_mfma_f32_32x32x16_bf16 v[48:63], v[72:75], v[204:207], v[48:63]
	ds_read_b64_tr_b16 v[204:205], v199 offset:0x500
	ds_read_b64_tr_b16 v[206:207], v199 offset:0x1400
	v_max3_f32 v200, v200, v92, v93
	v_max3_f32 v200, v200, v94, v95
	s_waitcnt lgkmcnt(5)
	v_mfma_f32_32x32x16_bf16 v[48:63], v[68:71], v[208:211], v[48:63]
	ds_read_b64_tr_b16 v[208:209], v199 offset:0x1500
	ds_read_b64_tr_b16 v[210:211], v199 offset:0x2400
	ds_read_b64_tr_b16 v[212:213], v199 offset:0x2500
	ds_read_b64_tr_b16 v[222:223], v199 offset:0x3400
	ds_read_b64_tr_b16 v[224:225], v199 offset:0x3500
	s_waitcnt lgkmcnt(8)
	v_mfma_f32_32x32x16_bf16 v[48:63], v[76:79], v[226:229], v[48:63]
	s_waitcnt lgkmcnt(6)
	v_mfma_f32_32x32x16_bf16 v[32:47], v[64:67], v[202:205], v[32:47]
	v_cmp_ge_f32_e32 vcc, s63, v200
	s_cmp_eq_u64 vcc, exec
	s_waitcnt lgkmcnt(4)
	v_mfma_f32_32x32x16_bf16 v[32:47], v[72:75], v[206:209], v[32:47]
	s_waitcnt lgkmcnt(2)
	v_mfma_f32_32x32x16_bf16 v[32:47], v[68:71], v[210:213], v[32:47]
	s_waitcnt lgkmcnt(0)
	v_mfma_f32_32x32x16_bf16 v[32:47], v[76:79], v[222:225], v[32:47]
	s_cbranch_scc0 .LBB0_438
	v_mov_b32_e32 v200, 1.0

.LBB0_431:
	v_add_u32_e32 v203, s16, v181
	ds_read_b64_tr_b16 v[204:205], v203 offset:0
	ds_read_b64_tr_b16 v[206:207], v203 offset:0x100
	ds_read_b64_tr_b16 v[208:209], v203 offset:0x1000
	ds_read_b64_tr_b16 v[210:211], v203 offset:0x1100
	ds_read_b64_tr_b16 v[222:223], v203 offset:0x2000
	ds_read_b64_tr_b16 v[224:225], v203 offset:0x2100
	ds_read_b64_tr_b16 v[226:227], v203 offset:0x3000
	ds_read_b64_tr_b16 v[228:229], v203 offset:0x3100
	s_waitcnt lgkmcnt(0)
	s_nop 0
	v_mfma_f32_32x32x16_bf16 v[0:15], v[88:91], v[204:207], v[0:15]
	v_max_f32_e32 v199, v96, v97
	ds_read_b64_tr_b16 v[204:205], v203 offset:0x200
	ds_read_b64_tr_b16 v[206:207], v203 offset:0x300
	v_max3_f32 v199, v199, v98, v99
	v_max3_f32 v199, v199, v100, v101
	v_mfma_f32_32x32x16_bf16 v[0:15], v[92:95], v[208:211], v[0:15]
	ds_read_b64_tr_b16 v[208:209], v203 offset:0x1200
	ds_read_b64_tr_b16 v[210:211], v203 offset:0x1300
	v_max3_f32 v199, v199, v102, v103
	v_max3_f32 v199, v199, v104, v105
	v_max3_f32 v199, v199, v106, v107
	v_max3_f32 v199, v199, v108, v109
	v_max3_f32 v199, v199, v110, v111
	v_mfma_f32_32x32x16_bf16 v[0:15], v[80:83], v[222:225], v[0:15]
	ds_read_b64_tr_b16 v[222:223], v203 offset:0x2200
	ds_read_b64_tr_b16 v[224:225], v203 offset:0x2300
	ds_read_b64_tr_b16 v[230:231], v203 offset:0x3200
	ds_read_b64_tr_b16 v[232:233], v203 offset:0x3300
	v_mfma_f32_32x32x16_bf16 v[0:15], v[84:87], v[226:229], v[0:15]
	s_waitcnt lgkmcnt(6)
	v_mfma_f32_32x32x16_bf16 v[48:63], v[88:91], v[204:207], v[48:63]
	v_max3_f32 v199, v199, v64, v65
	v_max3_f32 v199, v199, v66, v67
	ds_read_b64_tr_b16 v[206:207], v203 offset:0x400
	v_max3_f32 v199, v199, v68, v69
	v_max3_f32 v199, v199, v70, v71
	v_max3_f32 v199, v199, v72, v73
	v_max3_f32 v199, v199, v74, v75
	s_waitcnt lgkmcnt(5)
	v_mfma_f32_32x32x16_bf16 v[48:63], v[92:95], v[208:211], v[48:63]
	ds_read_b64_tr_b16 v[208:209], v203 offset:0x500
	ds_read_b64_tr_b16 v[210:211], v203 offset:0x1400
	ds_read_b64_tr_b16 v[212:213], v203 offset:0x1500
	v_max3_f32 v199, v199, v76, v77
	v_max3_f32 v199, v199, v78, v79
	v_mov_b32_e32 v204, v199
	s_waitcnt lgkmcnt(6)
	v_mfma_f32_32x32x16_bf16 v[48:63], v[80:83], v[222:225], v[48:63]
	ds_read_b64_tr_b16 v[222:223], v203 offset:0x2400
	ds_read_b64_tr_b16 v[224:225], v203 offset:0x2500
	ds_read_b64_tr_b16 v[226:227], v203 offset:0x3400
	ds_read_b64_tr_b16 v[228:229], v203 offset:0x3500
	s_waitcnt lgkmcnt(8)
	v_mfma_f32_32x32x16_bf16 v[48:63], v[84:87], v[230:233], v[48:63]
	s_waitcnt lgkmcnt(6)
	v_mfma_f32_32x32x16_bf16 v[32:47], v[88:91], v[206:209], v[32:47]
	v_cmp_ge_f32_e32 vcc, s63, v204
	s_cmp_eq_u64 vcc, exec
	v_mov_b32_e32 v199, 1.0
	s_waitcnt lgkmcnt(4)
	v_mfma_f32_32x32x16_bf16 v[32:47], v[92:95], v[210:213], v[32:47]
	s_waitcnt lgkmcnt(2)
	v_mfma_f32_32x32x16_bf16 v[32:47], v[80:83], v[222:225], v[32:47]
	s_waitcnt lgkmcnt(0)
	v_mfma_f32_32x32x16_bf16 v[32:47], v[84:87], v[226:229], v[32:47]
	s_cbranch_scc0 .LBB0_439

.LBB0_438:
	v_mov_b32_e32 v201, v200
	s_nop 1
	v_permlane32_swap_b32_e32 v200, v201
	v_max_f32_e32 v200, v200, v201
	v_max_f32_e32 v202, 0, v200
	v_exp_f32_e64 v200, -v202
	v_add_f32_e32 v195, v195, v202
	v_pk_add_f32 v[96:97], v[96:97], v[202:203] op_sel_hi:[1,0] neg_lo:[0,1] neg_hi:[0,1]
	v_pk_add_f32 v[98:99], v[98:99], v[202:203] op_sel_hi:[1,0] neg_lo:[0,1] neg_hi:[0,1]
	v_pk_add_f32 v[100:101], v[100:101], v[202:203] op_sel_hi:[1,0] neg_lo:[0,1] neg_hi:[0,1]
	v_pk_add_f32 v[102:103], v[102:103], v[202:203] op_sel_hi:[1,0] neg_lo:[0,1] neg_hi:[0,1]
	v_pk_add_f32 v[104:105], v[104:105], v[202:203] op_sel_hi:[1,0] neg_lo:[0,1] neg_hi:[0,1]
	v_pk_add_f32 v[106:107], v[106:107], v[202:203] op_sel_hi:[1,0] neg_lo:[0,1] neg_hi:[0,1]
	v_pk_add_f32 v[108:109], v[108:109], v[202:203] op_sel_hi:[1,0] neg_lo:[0,1] neg_hi:[0,1]
	v_pk_add_f32 v[110:111], v[110:111], v[202:203] op_sel_hi:[1,0] neg_lo:[0,1] neg_hi:[0,1]
	v_sub_f32_e32 v95, v95, v202
	v_sub_f32_e32 v94, v94, v202
	v_sub_f32_e32 v93, v93, v202
	v_sub_f32_e32 v92, v92, v202
	v_sub_f32_e32 v91, v91, v202
	v_sub_f32_e32 v90, v90, v202
	v_sub_f32_e32 v89, v89, v202
	v_sub_f32_e32 v88, v88, v202
	v_sub_f32_e32 v87, v87, v202
	v_sub_f32_e32 v86, v86, v202
	v_sub_f32_e32 v85, v85, v202
	v_sub_f32_e32 v84, v84, v202
	v_sub_f32_e32 v83, v83, v202
	v_sub_f32_e32 v82, v82, v202
	v_sub_f32_e32 v81, v81, v202
	v_sub_f32_e32 v80, v80, v202
	s_branch .LBB0_425
.LBB0_439:
	v_mov_b32_e32 v199, v204
	s_nop 1
	v_permlane32_swap_b32_e32 v204, v199
	v_max_f32_e32 v199, v204, v199
	v_max_f32_e32 v204, 0, v199
	v_exp_f32_e64 v199, -v204
	v_add_f32_e32 v195, v195, v204
	v_pk_add_f32 v[96:97], v[96:97], v[204:205] op_sel_hi:[1,0] neg_lo:[0,1] neg_hi:[0,1]
	v_pk_add_f32 v[98:99], v[98:99], v[204:205] op_sel_hi:[1,0] neg_lo:[0,1] neg_hi:[0,1]
	v_pk_add_f32 v[100:101], v[100:101], v[204:205] op_sel_hi:[1,0] neg_lo:[0,1] neg_hi:[0,1]
	v_pk_add_f32 v[102:103], v[102:103], v[204:205] op_sel_hi:[1,0] neg_lo:[0,1] neg_hi:[0,1]
	v_pk_add_f32 v[104:105], v[104:105], v[204:205] op_sel_hi:[1,0] neg_lo:[0,1] neg_hi:[0,1]
	v_pk_add_f32 v[106:107], v[106:107], v[204:205] op_sel_hi:[1,0] neg_lo:[0,1] neg_hi:[0,1]
	v_pk_add_f32 v[108:109], v[108:109], v[204:205] op_sel_hi:[1,0] neg_lo:[0,1] neg_hi:[0,1]
	v_pk_add_f32 v[110:111], v[110:111], v[204:205] op_sel_hi:[1,0] neg_lo:[0,1] neg_hi:[0,1]
	v_sub_f32_e32 v79, v79, v204
	v_sub_f32_e32 v78, v78, v204
	v_sub_f32_e32 v77, v77, v204
	v_sub_f32_e32 v76, v76, v204
	v_sub_f32_e32 v75, v75, v204
	v_sub_f32_e32 v74, v74, v204
	v_sub_f32_e32 v73, v73, v204
	v_sub_f32_e32 v72, v72, v204
	v_sub_f32_e32 v71, v71, v204
	v_sub_f32_e32 v70, v70, v204
	v_sub_f32_e32 v69, v69, v204
	v_sub_f32_e32 v68, v68, v204
	v_sub_f32_e32 v67, v67, v204
	v_sub_f32_e32 v66, v66, v204
	v_sub_f32_e32 v65, v65, v204
	v_sub_f32_e32 v64, v64, v204
	s_branch .LBB0_432
